# speedup vs baseline: 1.0003x; 1.0003x over previous
; __device__ __forceinline__ int otid() { int t = threadIdx.x; asm volatile("" : "+v"(t)); return t; }
; __device__ __forceinline__ void ph_indexer(const Params& p, char* shm) {
;   const int tid = otid(), wid = __builtin_amdgcn_readfirstlane(tid >> 6), lane = tid & 63, col = lane & 31, half = lane >> 5;
;   char* wtab = shm + 65536;
;   for (int item = blockIdx.x; item < 512; item += gridDim.x) {
;     const int b = item >> 8, cp = item & 255;
;     for (int side = 0; side < 2; ++side) {
;       const int chunk = side ? 511 - cp : cp;
;       const int t0 = chunk * 16, nst = (t0 + 16 + 127) >> 7;
;       const size_t rowb = (size_t)b * L + t0;
;       const u16* kib = p.KI + (size_t)b * L * 128;
;       s16x8 Aq[2][8];
; #pragma unroll
;       for (int q = 0; q < 2; ++q) {
;         const u16* qp = p.P + (rowb + wid * 2 + q) * NP + QI_OFF + col * 128 + half * 8;
; __global__ void __launch_bounds__(512, 2) mega(Params p, int ph0, int ph1) {
;     ...
;       const int l = (ph - 1) >> 3, s = (ph - 1) & 7;
;       const int nrep = ((REPMASK >> s) & 1u) ? 2 : 1;
;       for (int rep = 0; rep < nrep; ++rep)
;       switch (s) {
;         case 0: ph_proj(p, l, shm); break;
;         case 1: ph_post(p, l, shm); break;
;         case 2:
;           for (int r2 = 0; r2 < (((REPMASK >> 9) & 1u) ? 2 : 1); ++r2) { ph_indexer(p, shm); __syncthreads(); }
.LBB0_911:
	s_andn2_b64 vcc, exec, s[0:1]
	s_cbranch_vccnz .LBB0_1745
	v_readlane_b32 s0, v245, 53
	s_cmp_lt_i32 s0, 2
	s_mov_b64 s[0:1], -1
	s_cbranch_scc1 .LBB0_954
	v_readlane_b32 s0, v245, 53
	s_cmp_lt_i32 s0, 3
	s_cbranch_scc0 .LBB0_953
	v_readlane_b32 s0, v246, 30
	v_mov_b32_e32 v0, v204
	v_readlane_b32 s1, v246, 31
	s_andn2_b64 vcc, exec, s[0:1]
	v_readfirstlane_b32 s2, v0
	s_cbranch_vccnz .LBB0_947
	s_ashr_i32 s3, s2, 6
	s_lshl_b32 s4, s3, 2
	v_and_b32_e32 v3, 31, v0
	s_ashr_i32 s2, s2, 7
	s_and_b32 s4, s4, 4
	v_lshl_or_b32 v118, s2, 5, v3
	s_lshl_b32 s26, s2, 13
	s_or_b32 s2, s4, 1
	v_and_b32_e32 v2, 63, v0
	v_lshrrev_b32_e32 v1, 2, v0
	s_lshl_b32 s30, s2, 4
	s_lshl_b32 s31, s2, 10
	s_or_b32 s2, s4, 2
	v_readlane_b32 s8, v246, 0
	s_lshl_b32 s24, s3, 1
	v_and_b32_e32 v116, 8, v1
	s_movk_i32 s0, 0x100
	v_ashrrev_i32_e32 v1, 31, v0
	v_ashrrev_i32_e32 v119, 31, v118
	s_lshl_b32 s27, s3, 7
	s_lshl_b32 s34, s2, 4
	s_lshl_b32 s35, s2, 10
	s_or_b32 s2, s4, 3
	v_readlane_b32 s9, v246, 1
	v_readlane_b32 s10, v246, 2
	v_readlane_b32 s11, v246, 3
	v_lshlrev_b32_e32 v32, 2, v2
	s_ashr_i32 s25, s24, 31
	v_lshlrev_b32_e32 v114, 7, v3
	v_cmp_gt_i32_e64 s[0:1], s0, v0
	v_lshl_add_u32 v115, v0, 2, v217
	v_lshlrev_b64 v[120:121], 8, v[118:119]
	s_add_i32 s27, s27, 0x10000
	v_lshlrev_b32_e32 v117, 4, v2
	v_cmp_gt_u32_e64 s[6:7], 32, v2
	s_lshl_b32 s28, s4, 4
	s_lshl_b32 s29, s4, 10
	s_lshl_b32 s36, s2, 4
	s_lshl_b32 s37, s2, 10
	v_lshl_add_u64 v[122:123], v[0:1], 3, s[8:9]
	v_lshl_add_u64 v[124:125], s[10:11], 0, v[32:33]
	v_lshlrev_b32_e32 v32, 1, v116
	s_cmp_ge_u32 s3, 4
	s_cselect_b32 s70, 1, 0
	v_and_b32_e32 v114, 15, v204
	v_and_b32_e32 v117, 48, v204
	v_lshlrev_b32_e32 v114, 7, v114
	v_lshrrev_b32_e32 v0, 1, v117
	v_or_b32_e32 v114, v114, v0
	v_and_b32_e32 v0, 15, v204
	v_lshlrev_b32_e32 v0, 4, v0
	v_lshl_or_b32 v117, v117, 5, v0
	s_mov_b32 s38, s86
	s_branch .LBB0_917

; #define WAIT_V0() asm volatile("s_waitcnt vmcnt(0)" ::: "memory")
; #define WAIT_L0() asm volatile("s_waitcnt lgkmcnt(0)" ::: "memory")
; __device__ __forceinline__ void ph_indexer(const Params& p, char* shm) {
;     ...
;       h16x2 wq[2][8];
;       IDX_STAGE(0, 0);
;       for (int st = 0; st < nst; ++st) {
;         if (st == 0) WAIT_V0(); else asm volatile("s_waitcnt vmcnt(4)" ::: "memory");
;         WAIT_L0();
;         __builtin_amdgcn_s_barrier();
;         if (st + 1 < nst) IDX_STAGE((st + 1) & 1, st + 1);
;         if (st == 0) {
; #pragma unroll
;           for (int q = 0; q < 2; ++q)
; #pragma unroll
;             for (int i4 = 0; i4 < 4; ++i4) {
;               const uint2 u = *(const uint2*)(wtab + (wid * 2 + q) * 64 + (half * 4 + 8 * i4) * 2);
;               wq[q][2 * i4] = __builtin_bit_cast(h16x2, u.x);
;               wq[q][2 * i4 + 1] = __builtin_bit_cast(h16x2, u.y);
;             }
;         }
;         const char* kbuf = shm + (st & 1) * 32768;
; #pragma unroll 1
;         for (int ktp = 0; ktp < 2; ++ktp) {
;           float pr0[2], pr1[2];
;     ...
;           IDX_TILE(ktp * 2, pr0);
;           __builtin_amdgcn_sched_barrier(0);
;           IDX_TILE(ktp * 2 + 1, pr1);
.Lidx_join_s0:
	v_lshl_add_u64 v[232:233], v[138:139], 0, s[16:17]
	v_lshl_add_u64 v[234:235], v[138:139], 0, s[18:19]
	v_mfma_f32_16x16x32_bf16 v[16:19], v[106:109], v[172:175], 0
	v_mfma_f32_16x16x32_bf16 v[24:27], v[94:97], v[172:175], 0
	ds_read_b128 v[172:175], v129 offset:8192
	v_mfma_f32_16x16x32_bf16 v[20:23], v[106:109], v[176:179], 0
	s_cmp_ge_u32 s22, s44
	s_cbranch_scc1 .Lidx_nostage_s0_0_0
	s_cmp_eq_u32 s70, 1
	s_cbranch_scc1 .Lidx_nostage_s0_0_0
	v_lshl_add_u32 v236, s22, 7, v118
	v_ashrrev_i32_e32 v237, 31, v236
	s_lshl_b32 s3, s22, 15
	v_lshlrev_b64 v[236:237], 8, v[236:237]
	s_and_b32 s3, s3, 0x8000
	v_lshl_add_u64 v[236:237], v[126:127], 0, v[236:237]
	s_add_i32 s23, s26, s3
	s_mov_b32 s3, s5
	v_lshl_add_u64 v[238:239], v[236:237], 0, s[2:3]
	s_add_i32 m0, s23, s29
	s_mov_b32 s9, s5
	global_load_lds_dwordx4 v[238:239], off
.Lidx_nostage_s0_0_0:
	v_mfma_f32_16x16x32_bf16 v[28:31], v[94:97], v[176:179], 0
	ds_read_b128 v[176:179], v129 offset:8448
	s_cmp_ge_u32 s22, s44
	s_cbranch_scc1 .Lidx_nostage_s0_0_1
	s_cmp_eq_u32 s70, 1
	s_cbranch_scc1 .Lidx_nostage_s0_0_1
	v_lshl_add_u64 v[238:239], v[236:237], 0, s[8:9]
	s_add_i32 m0, s23, s31
	s_mov_b32 s11, s5
	global_load_lds_dwordx4 v[238:239], off
.Lidx_nostage_s0_0_1:
	v_mfma_f32_16x16x32_bf16 v[16:19], v[82:85], v[180:183], v[16:19]
	s_cmp_ge_u32 s22, s44
	s_cbranch_scc1 .Lidx_nostage_s0_0_2
	s_cmp_eq_u32 s70, 1
	s_cbranch_scc1 .Lidx_nostage_s0_0_2
	v_lshl_add_u64 v[238:239], v[236:237], 0, s[10:11]
	s_add_i32 m0, s23, s35
	s_mov_b32 s13, s5
	global_load_lds_dwordx4 v[238:239], off
.Lidx_nostage_s0_0_2:
	v_max_i32_e32 v224, 0, v0
	v_fma_f32 v200, v224, v140, 0
	v_mfma_f32_16x16x32_bf16 v[24:27], v[98:101], v[180:183], v[24:27]
	ds_read_b128 v[180:183], v129 offset:10240
	s_cmp_ge_u32 s22, s44
	s_cbranch_scc1 .Lidx_nostage_s0_0_3
	s_cmp_eq_u32 s70, 1
	s_cbranch_scc1 .Lidx_nostage_s0_0_3
	v_lshl_add_u64 v[236:237], v[236:237], 0, s[12:13]
	s_add_i32 m0, s23, s37
	s_nop 0
	global_load_lds_dwordx4 v[236:237], off
.Lidx_nostage_s0_0_3:
	v_max_i32_e32 v225, 0, v1
	v_fmac_f32_e32 v200, v225, v141
	v_mfma_f32_16x16x32_bf16 v[20:23], v[82:85], v[184:187], v[20:23]
	v_max_i32_e32 v224, 0, v2
	v_fmac_f32_e32 v200, v224, v142
	v_max_i32_e32 v225, 0, v3
	v_mfma_f32_16x16x32_bf16 v[28:31], v[98:101], v[184:187], v[28:31]
	ds_read_b128 v[184:187], v129 offset:10496
	v_fmac_f32_e32 v200, v225, v143
	v_max_i32_e32 v224, 0, v8
	v_fmac_f32_e32 v200, v224, v144
	v_mfma_f32_16x16x32_bf16 v[16:19], v[86:89], v[188:191], v[16:19]
	v_max_i32_e32 v225, 0, v9
	v_fmac_f32_e32 v200, v225, v145
	v_max_i32_e32 v224, 0, v10
	v_mfma_f32_16x16x32_bf16 v[24:27], v[102:105], v[188:191], v[24:27]
	ds_read_b128 v[188:191], v129 offset:12288
	v_fmac_f32_e32 v200, v224, v146
	v_max_i32_e32 v225, 0, v11
	v_fmac_f32_e32 v200, v225, v147
	v_mfma_f32_16x16x32_bf16 v[20:23], v[86:89], v[192:195], v[20:23]
	v_max_i32_e32 v224, 0, v4
	v_fma_f32 v201, v224, v140, 0
	v_max_i32_e32 v225, 0, v5
	v_mfma_f32_16x16x32_bf16 v[28:31], v[102:105], v[192:195], v[28:31]
	ds_read_b128 v[192:195], v129 offset:12544
	v_fmac_f32_e32 v201, v225, v141
	v_max_i32_e32 v224, 0, v6
	v_fmac_f32_e32 v201, v224, v142
	v_mfma_f32_16x16x32_bf16 v[16:19], v[90:93], v[196:199], v[16:19]
	v_max_i32_e32 v225, 0, v7
	v_fmac_f32_e32 v201, v225, v143
	v_max_i32_e32 v224, 0, v12
	v_mfma_f32_16x16x32_bf16 v[24:27], v[110:113], v[196:199], v[24:27]
	ds_read_b128 v[196:199], v129 offset:14336
	v_fmac_f32_e32 v201, v224, v144
	v_max_i32_e32 v225, 0, v13
	v_fmac_f32_e32 v201, v225, v145
	v_mfma_f32_16x16x32_bf16 v[20:23], v[90:93], v[226:229], v[20:23]
	v_max_i32_e32 v224, 0, v14
	v_fmac_f32_e32 v201, v224, v146
	v_mfma_f32_16x16x32_bf16 v[28:31], v[110:113], v[226:229], v[28:31]
	ds_read_b128 v[226:229], v129 offset:14592
	v_max_i32_e32 v225, 0, v15
	v_fmac_f32_e32 v201, v225, v147
	s_waitcnt lgkmcnt(7)
	v_mfma_f32_16x16x32_bf16 v[0:3], v[74:77], v[172:175], 0
	v_mfma_f32_16x16x32_bf16 v[8:11], v[62:65], v[172:175], 0
	s_waitcnt lgkmcnt(6)
	v_mfma_f32_16x16x32_bf16 v[4:7], v[74:77], v[176:179], 0
	v_mfma_f32_16x16x32_bf16 v[12:15], v[62:65], v[176:179], 0
	v_max_i32_e32 v230, 0, v16
	v_fma_f32 v202, v230, v148, 0
	s_waitcnt lgkmcnt(5)
	v_mfma_f32_16x16x32_bf16 v[0:3], v[50:53], v[180:183], v[0:3]
	v_max_i32_e32 v231, 0, v17
	v_fmac_f32_e32 v202, v231, v149
	v_mfma_f32_16x16x32_bf16 v[8:11], v[66:69], v[180:183], v[8:11]
	v_max_i32_e32 v230, 0, v18
	v_fmac_f32_e32 v202, v230, v150
	s_waitcnt lgkmcnt(4)
	v_mfma_f32_16x16x32_bf16 v[4:7], v[50:53], v[184:187], v[4:7]
	v_max_i32_e32 v231, 0, v19
	v_fmac_f32_e32 v202, v231, v151
	v_mfma_f32_16x16x32_bf16 v[12:15], v[66:69], v[184:187], v[12:15]
	v_max_i32_e32 v230, 0, v24
	v_fmac_f32_e32 v202, v230, v152
	s_waitcnt lgkmcnt(3)
	v_mfma_f32_16x16x32_bf16 v[0:3], v[54:57], v[188:191], v[0:3]
	v_max_i32_e32 v231, 0, v25
	v_fmac_f32_e32 v202, v231, v153
	v_mfma_f32_16x16x32_bf16 v[8:11], v[70:73], v[188:191], v[8:11]
	v_max_i32_e32 v230, 0, v26
	v_fmac_f32_e32 v202, v230, v154
	v_max_i32_e32 v231, 0, v27
	s_waitcnt lgkmcnt(2)
	v_mfma_f32_16x16x32_bf16 v[4:7], v[54:57], v[192:195], v[4:7]
	v_fmac_f32_e32 v202, v231, v155
	v_max_i32_e32 v230, 0, v20
	v_fma_f32 v203, v230, v148, 0
	v_mfma_f32_16x16x32_bf16 v[12:15], v[70:73], v[192:195], v[12:15]
	v_max_i32_e32 v231, 0, v21
	v_fmac_f32_e32 v203, v231, v149
	v_max_i32_e32 v230, 0, v22
	s_waitcnt lgkmcnt(1)
	v_mfma_f32_16x16x32_bf16 v[0:3], v[58:61], v[196:199], v[0:3]
	v_fmac_f32_e32 v203, v230, v150
	v_max_i32_e32 v231, 0, v23
	v_fmac_f32_e32 v203, v231, v151
	v_mfma_f32_16x16x32_bf16 v[8:11], v[78:81], v[196:199], v[8:11]
	v_max_i32_e32 v230, 0, v28
	v_fmac_f32_e32 v203, v230, v152
	v_max_i32_e32 v231, 0, v29
	s_waitcnt lgkmcnt(0)
	v_mfma_f32_16x16x32_bf16 v[4:7], v[58:61], v[226:229], v[4:7]
	v_fmac_f32_e32 v203, v231, v153
	v_max_i32_e32 v230, 0, v30
	v_fmac_f32_e32 v203, v230, v154
	v_mfma_f32_16x16x32_bf16 v[12:15], v[78:81], v[226:229], v[12:15]
	v_max_i32_e32 v231, 0, v31
	v_fmac_f32_e32 v203, v231, v155
	v_mfma_f32_16x16x32_bf16 v[16:19], v[106:109], v[172:175], 0
	v_mfma_f32_16x16x32_bf16 v[24:27], v[94:97], v[172:175], 0
	ds_read_b128 v[172:175], v129 offset:16384
	v_mfma_f32_16x16x32_bf16 v[20:23], v[106:109], v[176:179], 0
	s_cmp_ge_u32 s22, s44
	s_cbranch_scc1 .Lidx_nostage_s0_1_0
	s_cmp_eq_u32 s70, 0
	s_cbranch_scc1 .Lidx_nostage_s0_1_0
	v_lshl_add_u32 v236, s22, 7, v118
	v_ashrrev_i32_e32 v237, 31, v236
	s_lshl_b32 s3, s22, 15
	v_lshlrev_b64 v[236:237], 8, v[236:237]
	s_and_b32 s3, s3, 0x8000
	v_lshl_add_u64 v[236:237], v[126:127], 0, v[236:237]
	s_add_i32 s23, s26, s3
	s_mov_b32 s3, s5
	v_lshl_add_u64 v[238:239], v[236:237], 0, s[2:3]
	s_add_i32 m0, s23, s29
	s_mov_b32 s9, s5
	global_load_lds_dwordx4 v[238:239], off
; __device__ __forceinline__ void ph_indexer(const Params& p, char* shm) {
;     ...
;           IDX_TILE(ktp * 2, pr0);
.Lidx_nostage_s0_1_0:
	v_mfma_f32_16x16x32_bf16 v[28:31], v[94:97], v[176:179], 0
	ds_read_b128 v[176:179], v129 offset:16640
	s_cmp_ge_u32 s22, s44
	s_cbranch_scc1 .Lidx_nostage_s0_1_1
	s_cmp_eq_u32 s70, 0
	s_cbranch_scc1 .Lidx_nostage_s0_1_1
	v_lshl_add_u64 v[238:239], v[236:237], 0, s[8:9]
	s_add_i32 m0, s23, s31
	s_mov_b32 s11, s5
	global_load_lds_dwordx4 v[238:239], off
.Lidx_nostage_s0_1_1:
	v_mfma_f32_16x16x32_bf16 v[16:19], v[82:85], v[180:183], v[16:19]
	s_cmp_ge_u32 s22, s44
	s_cbranch_scc1 .Lidx_nostage_s0_1_2
	s_cmp_eq_u32 s70, 0
	s_cbranch_scc1 .Lidx_nostage_s0_1_2
	v_lshl_add_u64 v[238:239], v[236:237], 0, s[10:11]
	s_add_i32 m0, s23, s35
	s_mov_b32 s13, s5
	global_load_lds_dwordx4 v[238:239], off
.Lidx_nostage_s0_1_2:
	v_max_i32_e32 v224, 0, v0
	v_fma_f32 v218, v224, v140, 0
	v_mfma_f32_16x16x32_bf16 v[24:27], v[98:101], v[180:183], v[24:27]
	ds_read_b128 v[180:183], v129 offset:18432
	s_cmp_ge_u32 s22, s44
	s_cbranch_scc1 .Lidx_nostage_s0_1_3
	s_cmp_eq_u32 s70, 0
	s_cbranch_scc1 .Lidx_nostage_s0_1_3
	v_lshl_add_u64 v[236:237], v[236:237], 0, s[12:13]
	s_add_i32 m0, s23, s37
	s_nop 0
	global_load_lds_dwordx4 v[236:237], off
.Lidx_nostage_s0_1_3:
	v_max_i32_e32 v225, 0, v1
	v_fmac_f32_e32 v218, v225, v141
	v_mfma_f32_16x16x32_bf16 v[20:23], v[82:85], v[184:187], v[20:23]
	v_max_i32_e32 v224, 0, v2
	v_fmac_f32_e32 v218, v224, v142
	v_max_i32_e32 v225, 0, v3
	v_mfma_f32_16x16x32_bf16 v[28:31], v[98:101], v[184:187], v[28:31]
	ds_read_b128 v[184:187], v129 offset:18688
	v_fmac_f32_e32 v218, v225, v143
	v_max_i32_e32 v224, 0, v8
	v_fmac_f32_e32 v218, v224, v144
	v_mfma_f32_16x16x32_bf16 v[16:19], v[86:89], v[188:191], v[16:19]
	v_max_i32_e32 v225, 0, v9
	v_fmac_f32_e32 v218, v225, v145
	v_max_i32_e32 v224, 0, v10
	v_mfma_f32_16x16x32_bf16 v[24:27], v[102:105], v[188:191], v[24:27]
	ds_read_b128 v[188:191], v129 offset:20480
	v_fmac_f32_e32 v218, v224, v146
	v_max_i32_e32 v225, 0, v11
	v_fmac_f32_e32 v218, v225, v147
	v_mfma_f32_16x16x32_bf16 v[20:23], v[86:89], v[192:195], v[20:23]
	v_max_i32_e32 v224, 0, v4
	v_fma_f32 v219, v224, v140, 0
	v_max_i32_e32 v225, 0, v5
	v_mfma_f32_16x16x32_bf16 v[28:31], v[102:105], v[192:195], v[28:31]
	ds_read_b128 v[192:195], v129 offset:20736
	v_fmac_f32_e32 v219, v225, v141
	v_max_i32_e32 v224, 0, v6
	v_fmac_f32_e32 v219, v224, v142
	v_mfma_f32_16x16x32_bf16 v[16:19], v[90:93], v[196:199], v[16:19]
	v_max_i32_e32 v225, 0, v7
	v_fmac_f32_e32 v219, v225, v143
	v_max_i32_e32 v224, 0, v12
	v_mfma_f32_16x16x32_bf16 v[24:27], v[110:113], v[196:199], v[24:27]
	ds_read_b128 v[196:199], v129 offset:22528
	v_fmac_f32_e32 v219, v224, v144
	v_max_i32_e32 v225, 0, v13
	v_fmac_f32_e32 v219, v225, v145
	v_mfma_f32_16x16x32_bf16 v[20:23], v[90:93], v[226:229], v[20:23]
	v_max_i32_e32 v224, 0, v14
	v_fmac_f32_e32 v219, v224, v146
	v_mfma_f32_16x16x32_bf16 v[28:31], v[110:113], v[226:229], v[28:31]
	ds_read_b128 v[226:229], v129 offset:22784
	v_max_i32_e32 v225, 0, v15
	v_fmac_f32_e32 v219, v225, v147
	s_waitcnt lgkmcnt(7)
	v_mfma_f32_16x16x32_bf16 v[0:3], v[74:77], v[172:175], 0
	v_mfma_f32_16x16x32_bf16 v[8:11], v[62:65], v[172:175], 0
	s_waitcnt lgkmcnt(6)
	v_mfma_f32_16x16x32_bf16 v[4:7], v[74:77], v[176:179], 0
	v_mfma_f32_16x16x32_bf16 v[12:15], v[62:65], v[176:179], 0
	v_max_i32_e32 v230, 0, v16
	v_fma_f32 v220, v230, v148, 0
	s_waitcnt lgkmcnt(5)
	v_mfma_f32_16x16x32_bf16 v[0:3], v[50:53], v[180:183], v[0:3]
	v_max_i32_e32 v231, 0, v17
	v_fmac_f32_e32 v220, v231, v149
	v_mfma_f32_16x16x32_bf16 v[8:11], v[66:69], v[180:183], v[8:11]
	v_max_i32_e32 v230, 0, v18
	v_fmac_f32_e32 v220, v230, v150
	s_waitcnt lgkmcnt(4)
	v_mfma_f32_16x16x32_bf16 v[4:7], v[50:53], v[184:187], v[4:7]
	v_max_i32_e32 v231, 0, v19
	v_fmac_f32_e32 v220, v231, v151
	v_mfma_f32_16x16x32_bf16 v[12:15], v[66:69], v[184:187], v[12:15]
	v_max_i32_e32 v230, 0, v24
	v_fmac_f32_e32 v220, v230, v152
	s_waitcnt lgkmcnt(3)
	v_mfma_f32_16x16x32_bf16 v[0:3], v[54:57], v[188:191], v[0:3]
	v_max_i32_e32 v231, 0, v25
	v_fmac_f32_e32 v220, v231, v153
	v_mfma_f32_16x16x32_bf16 v[8:11], v[70:73], v[188:191], v[8:11]
	v_max_i32_e32 v230, 0, v26
	v_fmac_f32_e32 v220, v230, v154
	v_max_i32_e32 v231, 0, v27
	s_waitcnt lgkmcnt(2)
	v_mfma_f32_16x16x32_bf16 v[4:7], v[54:57], v[192:195], v[4:7]
	v_fmac_f32_e32 v220, v231, v155
	v_max_i32_e32 v230, 0, v20
	v_fma_f32 v221, v230, v148, 0
	v_mfma_f32_16x16x32_bf16 v[12:15], v[70:73], v[192:195], v[12:15]
	v_max_i32_e32 v231, 0, v21
	v_fmac_f32_e32 v221, v231, v149
	v_max_i32_e32 v230, 0, v22
	s_waitcnt lgkmcnt(1)
	v_mfma_f32_16x16x32_bf16 v[0:3], v[58:61], v[196:199], v[0:3]
	v_fmac_f32_e32 v221, v230, v150
	v_max_i32_e32 v231, 0, v23
	v_fmac_f32_e32 v221, v231, v151
	v_mfma_f32_16x16x32_bf16 v[8:11], v[78:81], v[196:199], v[8:11]
	v_max_i32_e32 v230, 0, v28
	v_fmac_f32_e32 v221, v230, v152
	v_max_i32_e32 v231, 0, v29
	s_waitcnt lgkmcnt(0)
; __device__ __forceinline__ void ph_indexer(const Params& p, char* shm) {
;     ...
;           IDX_TILE(ktp * 2, pr0);
;           __builtin_amdgcn_sched_barrier(0);
;           IDX_TILE(ktp * 2 + 1, pr1);
;           __builtin_amdgcn_sched_barrier(0);
;     ...
; #pragma unroll
;           for (int q = 0; q < 2; ++q) {
;             const float mine = half ? pr1[q] : pr0[q];
;             const float send = half ? pr0[q] : pr1[q];
;             const float recv = __shfl_xor(send, 32);
;             p.SC[(rowb + wid * 2 + q) * L + st * 128 + ktp * 64 + lane] = mine + recv;
	v_mfma_f32_16x16x32_bf16 v[4:7], v[58:61], v[226:229], v[4:7]
	v_fmac_f32_e32 v221, v231, v153
	v_max_i32_e32 v230, 0, v30
	v_fmac_f32_e32 v221, v230, v154
	v_mfma_f32_16x16x32_bf16 v[12:15], v[78:81], v[226:229], v[12:15]
	v_max_i32_e32 v231, 0, v31
	v_fmac_f32_e32 v221, v231, v155
	v_mfma_f32_16x16x32_bf16 v[16:19], v[106:109], v[172:175], 0
	s_nop 1
	v_permlane16_swap_b32_e32 v200, v201
	v_permlane16_swap_b32_e32 v218, v219
	v_permlane16_swap_b32_e32 v202, v203
	v_mfma_f32_16x16x32_bf16 v[24:27], v[94:97], v[172:175], 0
	ds_read_b128 v[172:175], v129 offset:24576
	v_permlane16_swap_b32_e32 v220, v221
	v_add_f32_e32 v200, v200, v201
	v_add_f32_e32 v218, v218, v219
	v_add_f32_e32 v202, v202, v203
	v_mfma_f32_16x16x32_bf16 v[20:23], v[106:109], v[176:179], 0
	v_add_f32_e32 v220, v220, v221
	s_nop 1
	v_permlane32_swap_b32_e32 v200, v218
	v_permlane32_swap_b32_e32 v202, v220
	v_mfma_f32_16x16x32_bf16 v[28:31], v[94:97], v[176:179], 0
	ds_read_b128 v[176:179], v129 offset:24832
	v_add_f32_e32 v200, v200, v218
	v_add_f32_e32 v202, v202, v220
	global_store_dword v[232:233], v200, off nt
	global_store_dword v[234:235], v202, off nt
	v_mfma_f32_16x16x32_bf16 v[16:19], v[82:85], v[180:183], v[16:19]
	v_max_i32_e32 v224, 0, v0
	v_fma_f32 v222, v224, v140, 0
	v_mfma_f32_16x16x32_bf16 v[24:27], v[98:101], v[180:183], v[24:27]
	ds_read_b128 v[180:183], v129 offset:26624
	v_max_i32_e32 v225, 0, v1
	v_fmac_f32_e32 v222, v225, v141
	v_mfma_f32_16x16x32_bf16 v[20:23], v[82:85], v[184:187], v[20:23]
	v_max_i32_e32 v224, 0, v2
	v_fmac_f32_e32 v222, v224, v142
	v_max_i32_e32 v225, 0, v3
	v_mfma_f32_16x16x32_bf16 v[28:31], v[98:101], v[184:187], v[28:31]
	ds_read_b128 v[184:187], v129 offset:26880
	v_fmac_f32_e32 v222, v225, v143
	v_max_i32_e32 v224, 0, v8
	v_fmac_f32_e32 v222, v224, v144
	v_mfma_f32_16x16x32_bf16 v[16:19], v[86:89], v[188:191], v[16:19]
	v_max_i32_e32 v225, 0, v9
	v_fmac_f32_e32 v222, v225, v145
	v_max_i32_e32 v224, 0, v10
	v_mfma_f32_16x16x32_bf16 v[24:27], v[102:105], v[188:191], v[24:27]
	ds_read_b128 v[188:191], v129 offset:28672
	v_fmac_f32_e32 v222, v224, v146
	v_max_i32_e32 v225, 0, v11
	v_fmac_f32_e32 v222, v225, v147
	v_mfma_f32_16x16x32_bf16 v[20:23], v[86:89], v[192:195], v[20:23]
	v_max_i32_e32 v224, 0, v4
	v_fma_f32 v223, v224, v140, 0
	v_max_i32_e32 v225, 0, v5
	v_mfma_f32_16x16x32_bf16 v[28:31], v[102:105], v[192:195], v[28:31]
	ds_read_b128 v[192:195], v129 offset:28928
	v_fmac_f32_e32 v223, v225, v141
	v_max_i32_e32 v224, 0, v6
	v_fmac_f32_e32 v223, v224, v142
	v_mfma_f32_16x16x32_bf16 v[16:19], v[90:93], v[196:199], v[16:19]
	v_max_i32_e32 v225, 0, v7
	v_fmac_f32_e32 v223, v225, v143
	v_max_i32_e32 v224, 0, v12
	v_mfma_f32_16x16x32_bf16 v[24:27], v[110:113], v[196:199], v[24:27]
	ds_read_b128 v[196:199], v129 offset:30720
	v_fmac_f32_e32 v223, v224, v144
	v_max_i32_e32 v225, 0, v13
	v_fmac_f32_e32 v223, v225, v145
	v_mfma_f32_16x16x32_bf16 v[20:23], v[90:93], v[226:229], v[20:23]
	v_max_i32_e32 v224, 0, v14
	v_fmac_f32_e32 v223, v224, v146
	v_mfma_f32_16x16x32_bf16 v[28:31], v[110:113], v[226:229], v[28:31]
	ds_read_b128 v[226:229], v129 offset:30976
	v_max_i32_e32 v225, 0, v15
	v_fmac_f32_e32 v223, v225, v147
	s_waitcnt lgkmcnt(7)
	v_mfma_f32_16x16x32_bf16 v[0:3], v[74:77], v[172:175], 0
	v_mfma_f32_16x16x32_bf16 v[8:11], v[62:65], v[172:175], 0
	s_waitcnt lgkmcnt(6)
	v_mfma_f32_16x16x32_bf16 v[4:7], v[74:77], v[176:179], 0
	v_mfma_f32_16x16x32_bf16 v[12:15], v[62:65], v[176:179], 0
	v_max_i32_e32 v230, 0, v16
	v_fma_f32 v202, v230, v148, 0
	s_waitcnt lgkmcnt(5)
	v_mfma_f32_16x16x32_bf16 v[0:3], v[50:53], v[180:183], v[0:3]
	v_max_i32_e32 v231, 0, v17
	v_fmac_f32_e32 v202, v231, v149
	v_mfma_f32_16x16x32_bf16 v[8:11], v[66:69], v[180:183], v[8:11]
	v_max_i32_e32 v230, 0, v18
	v_fmac_f32_e32 v202, v230, v150
	s_waitcnt lgkmcnt(4)
; __device__ __forceinline__ void ph_indexer(const Params& p, char* shm) {
;     ...
;           IDX_TILE(ktp * 2, pr0);
;           __builtin_amdgcn_sched_barrier(0);
;           IDX_TILE(ktp * 2 + 1, pr1);
;           __builtin_amdgcn_sched_barrier(0);
;     ...
; #pragma unroll
;           for (int q = 0; q < 2; ++q) {
;             const float mine = half ? pr1[q] : pr0[q];
;             const float send = half ? pr0[q] : pr1[q];
;             const float recv = __shfl_xor(send, 32);
;             p.SC[(rowb + wid * 2 + q) * L + st * 128 + ktp * 64 + lane] = mine + recv;
;           }
;         }
	v_mfma_f32_16x16x32_bf16 v[4:7], v[50:53], v[184:187], v[4:7]
	v_max_i32_e32 v231, 0, v19
	v_fmac_f32_e32 v202, v231, v151
	v_mfma_f32_16x16x32_bf16 v[12:15], v[66:69], v[184:187], v[12:15]
	v_max_i32_e32 v230, 0, v24
	v_fmac_f32_e32 v202, v230, v152
	s_waitcnt lgkmcnt(3)
	v_mfma_f32_16x16x32_bf16 v[0:3], v[54:57], v[188:191], v[0:3]
	v_max_i32_e32 v231, 0, v25
	v_fmac_f32_e32 v202, v231, v153
	v_mfma_f32_16x16x32_bf16 v[8:11], v[70:73], v[188:191], v[8:11]
	v_max_i32_e32 v230, 0, v26
	v_fmac_f32_e32 v202, v230, v154
	v_max_i32_e32 v231, 0, v27
	s_waitcnt lgkmcnt(2)
	v_mfma_f32_16x16x32_bf16 v[4:7], v[54:57], v[192:195], v[4:7]
	v_fmac_f32_e32 v202, v231, v155
	v_max_i32_e32 v230, 0, v20
	v_fma_f32 v203, v230, v148, 0
	v_mfma_f32_16x16x32_bf16 v[12:15], v[70:73], v[192:195], v[12:15]
	v_max_i32_e32 v231, 0, v21
	v_fmac_f32_e32 v203, v231, v149
	v_max_i32_e32 v230, 0, v22
	s_waitcnt lgkmcnt(1)
	v_mfma_f32_16x16x32_bf16 v[0:3], v[58:61], v[196:199], v[0:3]
	v_fmac_f32_e32 v203, v230, v150
	v_max_i32_e32 v231, 0, v23
	v_fmac_f32_e32 v203, v231, v151
	v_mfma_f32_16x16x32_bf16 v[8:11], v[78:81], v[196:199], v[8:11]
	v_max_i32_e32 v230, 0, v28
	v_fmac_f32_e32 v203, v230, v152
	v_max_i32_e32 v231, 0, v29
	s_waitcnt lgkmcnt(0)
	v_mfma_f32_16x16x32_bf16 v[4:7], v[58:61], v[226:229], v[4:7]
	v_fmac_f32_e32 v203, v231, v153
	v_max_i32_e32 v230, 0, v30
	v_fmac_f32_e32 v203, v230, v154
	v_mfma_f32_16x16x32_bf16 v[12:15], v[78:81], v[226:229], v[12:15]
	v_max_i32_e32 v231, 0, v31
	v_fmac_f32_e32 v203, v231, v155
	v_mfma_f32_16x16x32_bf16 v[16:19], v[106:109], v[172:175], 0
	v_mfma_f32_16x16x32_bf16 v[24:27], v[94:97], v[172:175], 0
	v_mfma_f32_16x16x32_bf16 v[20:23], v[106:109], v[176:179], 0
	v_mfma_f32_16x16x32_bf16 v[28:31], v[94:97], v[176:179], 0
	v_mfma_f32_16x16x32_bf16 v[16:19], v[82:85], v[180:183], v[16:19]
	v_max_i32_e32 v224, 0, v0
	v_fma_f32 v218, v224, v140, 0
	v_mfma_f32_16x16x32_bf16 v[24:27], v[98:101], v[180:183], v[24:27]
	v_max_i32_e32 v225, 0, v1
	v_fmac_f32_e32 v218, v225, v141
	v_mfma_f32_16x16x32_bf16 v[20:23], v[82:85], v[184:187], v[20:23]
	v_max_i32_e32 v224, 0, v2
	v_fmac_f32_e32 v218, v224, v142
	v_max_i32_e32 v225, 0, v3
	v_mfma_f32_16x16x32_bf16 v[28:31], v[98:101], v[184:187], v[28:31]
	v_fmac_f32_e32 v218, v225, v143
	v_max_i32_e32 v224, 0, v8
	v_fmac_f32_e32 v218, v224, v144
	v_mfma_f32_16x16x32_bf16 v[16:19], v[86:89], v[188:191], v[16:19]
	v_max_i32_e32 v225, 0, v9
	v_fmac_f32_e32 v218, v225, v145
	v_max_i32_e32 v224, 0, v10
	v_mfma_f32_16x16x32_bf16 v[24:27], v[102:105], v[188:191], v[24:27]
	v_fmac_f32_e32 v218, v224, v146
	v_max_i32_e32 v225, 0, v11
	v_fmac_f32_e32 v218, v225, v147
	v_mfma_f32_16x16x32_bf16 v[20:23], v[86:89], v[192:195], v[20:23]
	v_max_i32_e32 v224, 0, v4
	v_fma_f32 v219, v224, v140, 0
	v_max_i32_e32 v225, 0, v5
	v_mfma_f32_16x16x32_bf16 v[28:31], v[102:105], v[192:195], v[28:31]
	v_fmac_f32_e32 v219, v225, v141
	v_max_i32_e32 v224, 0, v6
	v_fmac_f32_e32 v219, v224, v142
	v_mfma_f32_16x16x32_bf16 v[16:19], v[90:93], v[196:199], v[16:19]
	v_max_i32_e32 v225, 0, v7
	v_fmac_f32_e32 v219, v225, v143
	v_max_i32_e32 v224, 0, v12
	v_mfma_f32_16x16x32_bf16 v[24:27], v[110:113], v[196:199], v[24:27]
	v_fmac_f32_e32 v219, v224, v144
	v_max_i32_e32 v225, 0, v13
	v_fmac_f32_e32 v219, v225, v145
	v_mfma_f32_16x16x32_bf16 v[20:23], v[90:93], v[226:229], v[20:23]
	v_max_i32_e32 v224, 0, v14
	v_fmac_f32_e32 v219, v224, v146
	v_mfma_f32_16x16x32_bf16 v[28:31], v[110:113], v[226:229], v[28:31]
	v_max_i32_e32 v225, 0, v15
	v_fmac_f32_e32 v219, v225, v147
	s_cmp_lg_u32 s22, s44
	s_cbranch_scc0 .Lidx_flush_s0
	s_mov_b32 s4, s22
	s_branch .LBB0_920

; #define WAIT_V0() asm volatile("s_waitcnt vmcnt(0)" ::: "memory")
; #define WAIT_L0() asm volatile("s_waitcnt lgkmcnt(0)" ::: "memory")
; __device__ __forceinline__ void ph_indexer(const Params& p, char* shm) {
;     ...
;       h16x2 wq[2][8];
;       IDX_STAGE(0, 0);
;       for (int st = 0; st < nst; ++st) {
;         if (st == 0) WAIT_V0(); else asm volatile("s_waitcnt vmcnt(4)" ::: "memory");
;         WAIT_L0();
;         __builtin_amdgcn_s_barrier();
;         if (st + 1 < nst) IDX_STAGE((st + 1) & 1, st + 1);
;         if (st == 0) {
; #pragma unroll
;           for (int q = 0; q < 2; ++q)
; #pragma unroll
;             for (int i4 = 0; i4 < 4; ++i4) {
;               const uint2 u = *(const uint2*)(wtab + (wid * 2 + q) * 64 + (half * 4 + 8 * i4) * 2);
;               wq[q][2 * i4] = __builtin_bit_cast(h16x2, u.x);
;               wq[q][2 * i4 + 1] = __builtin_bit_cast(h16x2, u.y);
;             }
;         }
;         const char* kbuf = shm + (st & 1) * 32768;
; #pragma unroll 1
;         for (int ktp = 0; ktp < 2; ++ktp) {
;           float pr0[2], pr1[2];
;     ...
;           IDX_TILE(ktp * 2, pr0);
;           __builtin_amdgcn_sched_barrier(0);
;           IDX_TILE(ktp * 2 + 1, pr1);
.Lidx_join_s1:
	v_lshl_add_u64 v[228:229], v[110:111], 0, s[14:15]
	v_lshl_add_u64 v[230:231], v[110:111], 0, s[16:17]
	v_mfma_f32_16x16x32_bf16 v[184:187], v[90:93], v[160:163], 0
	v_mfma_f32_16x16x32_bf16 v[192:195], v[78:81], v[160:163], 0
	ds_read_b128 v[160:163], v112 offset:8192
	v_mfma_f32_16x16x32_bf16 v[188:191], v[90:93], v[164:167], 0
	s_cmp_ge_u32 s20, s22
	s_cbranch_scc1 .Lidx_nostage_s1_0_0
	s_cmp_eq_u32 s70, 1
	s_cbranch_scc1 .Lidx_nostage_s1_0_0
	v_lshl_add_u32 v236, s20, 7, v118
	v_ashrrev_i32_e32 v237, 31, v236
	s_lshl_b32 s3, s20, 15
	v_lshlrev_b64 v[236:237], 8, v[236:237]
	s_and_b32 s3, s3, 0x8000
	v_lshl_add_u64 v[236:237], v[126:127], 0, v[236:237]
	s_add_i32 s21, s26, s3
	s_mov_b32 s3, s5
	v_lshl_add_u64 v[238:239], v[236:237], 0, s[2:3]
	s_add_i32 m0, s21, s29
	s_mov_b32 s9, s5
	global_load_lds_dwordx4 v[238:239], off
.Lidx_nostage_s1_0_0:
	v_mfma_f32_16x16x32_bf16 v[196:199], v[78:81], v[164:167], 0
	ds_read_b128 v[164:167], v112 offset:8448
	s_cmp_ge_u32 s20, s22
	s_cbranch_scc1 .Lidx_nostage_s1_0_1
	s_cmp_eq_u32 s70, 1
	s_cbranch_scc1 .Lidx_nostage_s1_0_1
	v_lshl_add_u64 v[238:239], v[236:237], 0, s[8:9]
	s_add_i32 m0, s21, s31
	s_mov_b32 s11, s5
	global_load_lds_dwordx4 v[238:239], off
.Lidx_nostage_s1_0_1:
	v_mfma_f32_16x16x32_bf16 v[184:187], v[66:69], v[168:171], v[184:187]
	s_cmp_ge_u32 s20, s22
	s_cbranch_scc1 .Lidx_nostage_s1_0_2
	s_cmp_eq_u32 s70, 1
	s_cbranch_scc1 .Lidx_nostage_s1_0_2
	v_lshl_add_u64 v[238:239], v[236:237], 0, s[10:11]
	s_add_i32 m0, s21, s35
	s_mov_b32 s13, s5
	global_load_lds_dwordx4 v[238:239], off
.Lidx_nostage_s1_0_2:
	v_max_i32_e32 v224, 0, v0
	v_fma_f32 v200, v224, v128, 0
	v_mfma_f32_16x16x32_bf16 v[192:195], v[82:85], v[168:171], v[192:195]
	ds_read_b128 v[168:171], v112 offset:10240
	s_cmp_ge_u32 s20, s22
	s_cbranch_scc1 .Lidx_nostage_s1_0_3
	s_cmp_eq_u32 s70, 1
	s_cbranch_scc1 .Lidx_nostage_s1_0_3
	v_lshl_add_u64 v[236:237], v[236:237], 0, s[12:13]
	s_add_i32 m0, s21, s37
	s_nop 0
	global_load_lds_dwordx4 v[236:237], off
.Lidx_nostage_s1_0_3:
	v_max_i32_e32 v225, 0, v1
	v_fmac_f32_e32 v200, v225, v129
	v_mfma_f32_16x16x32_bf16 v[188:191], v[66:69], v[172:175], v[188:191]
	v_max_i32_e32 v224, 0, v2
	v_fmac_f32_e32 v200, v224, v130
	v_max_i32_e32 v225, 0, v3
	v_mfma_f32_16x16x32_bf16 v[196:199], v[82:85], v[172:175], v[196:199]
	ds_read_b128 v[172:175], v112 offset:10496
	v_fmac_f32_e32 v200, v225, v131
	v_max_i32_e32 v224, 0, v8
	v_fmac_f32_e32 v200, v224, v132
	v_mfma_f32_16x16x32_bf16 v[184:187], v[70:73], v[176:179], v[184:187]
	v_max_i32_e32 v225, 0, v9
	v_fmac_f32_e32 v200, v225, v133
	v_max_i32_e32 v224, 0, v10
	v_mfma_f32_16x16x32_bf16 v[192:195], v[86:89], v[176:179], v[192:195]
	ds_read_b128 v[176:179], v112 offset:12288
	v_fmac_f32_e32 v200, v224, v134
	v_max_i32_e32 v225, 0, v11
	v_fmac_f32_e32 v200, v225, v135
	v_mfma_f32_16x16x32_bf16 v[188:191], v[70:73], v[106:109], v[188:191]
	v_max_i32_e32 v224, 0, v4
	v_fma_f32 v201, v224, v128, 0
	v_max_i32_e32 v225, 0, v5
	v_mfma_f32_16x16x32_bf16 v[196:199], v[86:89], v[106:109], v[196:199]
	ds_read_b128 v[106:109], v112 offset:12544
	v_fmac_f32_e32 v201, v225, v129
	v_max_i32_e32 v224, 0, v6
	v_fmac_f32_e32 v201, v224, v130
	v_mfma_f32_16x16x32_bf16 v[184:187], v[74:77], v[102:105], v[184:187]
	v_max_i32_e32 v225, 0, v7
	v_fmac_f32_e32 v201, v225, v131
	v_max_i32_e32 v224, 0, v12
	v_mfma_f32_16x16x32_bf16 v[192:195], v[94:97], v[102:105], v[192:195]
	ds_read_b128 v[102:105], v112 offset:14336
	v_fmac_f32_e32 v201, v224, v132
	v_max_i32_e32 v225, 0, v13
	v_fmac_f32_e32 v201, v225, v133
	v_mfma_f32_16x16x32_bf16 v[188:191], v[74:77], v[98:101], v[188:191]
	v_max_i32_e32 v224, 0, v14
	v_fmac_f32_e32 v201, v224, v134
	v_mfma_f32_16x16x32_bf16 v[196:199], v[94:97], v[98:101], v[196:199]
	ds_read_b128 v[98:101], v112 offset:14592
	v_max_i32_e32 v225, 0, v15
	v_fmac_f32_e32 v201, v225, v135
	s_waitcnt lgkmcnt(7)
	v_mfma_f32_16x16x32_bf16 v[0:3], v[58:61], v[160:163], 0
	v_mfma_f32_16x16x32_bf16 v[8:11], v[28:31], v[160:163], 0
	s_waitcnt lgkmcnt(6)
	v_mfma_f32_16x16x32_bf16 v[4:7], v[58:61], v[164:167], 0
	v_mfma_f32_16x16x32_bf16 v[12:15], v[28:31], v[164:167], 0
	v_max_i32_e32 v226, 0, v184
	v_fma_f32 v202, v226, v136, 0
	s_waitcnt lgkmcnt(5)
	v_mfma_f32_16x16x32_bf16 v[0:3], v[16:19], v[168:171], v[0:3]
	v_max_i32_e32 v227, 0, v185
	v_fmac_f32_e32 v202, v227, v137
	v_mfma_f32_16x16x32_bf16 v[8:11], v[50:53], v[168:171], v[8:11]
	v_max_i32_e32 v226, 0, v186
	v_fmac_f32_e32 v202, v226, v138
	s_waitcnt lgkmcnt(4)
	v_mfma_f32_16x16x32_bf16 v[4:7], v[16:19], v[172:175], v[4:7]
	v_max_i32_e32 v227, 0, v187
	v_fmac_f32_e32 v202, v227, v139
	v_mfma_f32_16x16x32_bf16 v[12:15], v[50:53], v[172:175], v[12:15]
	v_max_i32_e32 v226, 0, v192
	v_fmac_f32_e32 v202, v226, v140
	s_waitcnt lgkmcnt(3)
	v_mfma_f32_16x16x32_bf16 v[0:3], v[20:23], v[176:179], v[0:3]
	v_max_i32_e32 v227, 0, v193
	v_fmac_f32_e32 v202, v227, v141
	v_mfma_f32_16x16x32_bf16 v[8:11], v[54:57], v[176:179], v[8:11]
	v_max_i32_e32 v226, 0, v194
	v_fmac_f32_e32 v202, v226, v142
	v_max_i32_e32 v227, 0, v195
	s_waitcnt lgkmcnt(2)
	v_mfma_f32_16x16x32_bf16 v[4:7], v[20:23], v[106:109], v[4:7]
	v_fmac_f32_e32 v202, v227, v143
	v_max_i32_e32 v226, 0, v188
	v_fma_f32 v203, v226, v136, 0
	v_mfma_f32_16x16x32_bf16 v[12:15], v[54:57], v[106:109], v[12:15]
	v_max_i32_e32 v227, 0, v189
	v_fmac_f32_e32 v203, v227, v137
	v_max_i32_e32 v226, 0, v190
	s_waitcnt lgkmcnt(1)
	v_mfma_f32_16x16x32_bf16 v[0:3], v[24:27], v[102:105], v[0:3]
	v_fmac_f32_e32 v203, v226, v138
	v_max_i32_e32 v227, 0, v191
	v_fmac_f32_e32 v203, v227, v139
	v_mfma_f32_16x16x32_bf16 v[8:11], v[62:65], v[102:105], v[8:11]
	v_max_i32_e32 v226, 0, v196
	v_fmac_f32_e32 v203, v226, v140
	v_max_i32_e32 v227, 0, v197
	s_waitcnt lgkmcnt(0)
	v_mfma_f32_16x16x32_bf16 v[4:7], v[24:27], v[98:101], v[4:7]
	v_fmac_f32_e32 v203, v227, v141
	v_max_i32_e32 v226, 0, v198
	v_fmac_f32_e32 v203, v226, v142
	v_mfma_f32_16x16x32_bf16 v[12:15], v[62:65], v[98:101], v[12:15]
	v_max_i32_e32 v227, 0, v199
	v_fmac_f32_e32 v203, v227, v143
	v_mfma_f32_16x16x32_bf16 v[184:187], v[90:93], v[160:163], 0
	v_mfma_f32_16x16x32_bf16 v[192:195], v[78:81], v[160:163], 0
	ds_read_b128 v[160:163], v112 offset:16384
	v_mfma_f32_16x16x32_bf16 v[188:191], v[90:93], v[164:167], 0
	s_cmp_ge_u32 s20, s22
	s_cbranch_scc1 .Lidx_nostage_s1_1_0
	s_cmp_eq_u32 s70, 0
	s_cbranch_scc1 .Lidx_nostage_s1_1_0
	v_lshl_add_u32 v236, s20, 7, v118
	v_ashrrev_i32_e32 v237, 31, v236
	s_lshl_b32 s3, s20, 15
	v_lshlrev_b64 v[236:237], 8, v[236:237]
	s_and_b32 s3, s3, 0x8000
	v_lshl_add_u64 v[236:237], v[126:127], 0, v[236:237]
	s_add_i32 s21, s26, s3
	s_mov_b32 s3, s5
	v_lshl_add_u64 v[238:239], v[236:237], 0, s[2:3]
	s_add_i32 m0, s21, s29
	s_mov_b32 s9, s5
	global_load_lds_dwordx4 v[238:239], off
; __device__ __forceinline__ void ph_indexer(const Params& p, char* shm) {
;     ...
;           IDX_TILE(ktp * 2, pr0);
.Lidx_nostage_s1_1_0:
	v_mfma_f32_16x16x32_bf16 v[196:199], v[78:81], v[164:167], 0
	ds_read_b128 v[164:167], v112 offset:16640
	s_cmp_ge_u32 s20, s22
	s_cbranch_scc1 .Lidx_nostage_s1_1_1
	s_cmp_eq_u32 s70, 0
	s_cbranch_scc1 .Lidx_nostage_s1_1_1
	v_lshl_add_u64 v[238:239], v[236:237], 0, s[8:9]
	s_add_i32 m0, s21, s31
	s_mov_b32 s11, s5
	global_load_lds_dwordx4 v[238:239], off
.Lidx_nostage_s1_1_1:
	v_mfma_f32_16x16x32_bf16 v[184:187], v[66:69], v[168:171], v[184:187]
	s_cmp_ge_u32 s20, s22
	s_cbranch_scc1 .Lidx_nostage_s1_1_2
	s_cmp_eq_u32 s70, 0
	s_cbranch_scc1 .Lidx_nostage_s1_1_2
	v_lshl_add_u64 v[238:239], v[236:237], 0, s[10:11]
	s_add_i32 m0, s21, s35
	s_mov_b32 s13, s5
	global_load_lds_dwordx4 v[238:239], off
.Lidx_nostage_s1_1_2:
	v_max_i32_e32 v224, 0, v0
	v_fma_f32 v218, v224, v128, 0
	v_mfma_f32_16x16x32_bf16 v[192:195], v[82:85], v[168:171], v[192:195]
	ds_read_b128 v[168:171], v112 offset:18432
	s_cmp_ge_u32 s20, s22
	s_cbranch_scc1 .Lidx_nostage_s1_1_3
	s_cmp_eq_u32 s70, 0
	s_cbranch_scc1 .Lidx_nostage_s1_1_3
	v_lshl_add_u64 v[236:237], v[236:237], 0, s[12:13]
	s_add_i32 m0, s21, s37
	s_nop 0
	global_load_lds_dwordx4 v[236:237], off
.Lidx_nostage_s1_1_3:
	v_max_i32_e32 v225, 0, v1
	v_fmac_f32_e32 v218, v225, v129
	v_mfma_f32_16x16x32_bf16 v[188:191], v[66:69], v[172:175], v[188:191]
	v_max_i32_e32 v224, 0, v2
	v_fmac_f32_e32 v218, v224, v130
	v_max_i32_e32 v225, 0, v3
	v_mfma_f32_16x16x32_bf16 v[196:199], v[82:85], v[172:175], v[196:199]
	ds_read_b128 v[172:175], v112 offset:18688
	v_fmac_f32_e32 v218, v225, v131
	v_max_i32_e32 v224, 0, v8
	v_fmac_f32_e32 v218, v224, v132
	v_mfma_f32_16x16x32_bf16 v[184:187], v[70:73], v[176:179], v[184:187]
	v_max_i32_e32 v225, 0, v9
	v_fmac_f32_e32 v218, v225, v133
	v_max_i32_e32 v224, 0, v10
	v_mfma_f32_16x16x32_bf16 v[192:195], v[86:89], v[176:179], v[192:195]
	ds_read_b128 v[176:179], v112 offset:20480
	v_fmac_f32_e32 v218, v224, v134
	v_max_i32_e32 v225, 0, v11
	v_fmac_f32_e32 v218, v225, v135
	v_mfma_f32_16x16x32_bf16 v[188:191], v[70:73], v[106:109], v[188:191]
	v_max_i32_e32 v224, 0, v4
	v_fma_f32 v219, v224, v128, 0
	v_max_i32_e32 v225, 0, v5
	v_mfma_f32_16x16x32_bf16 v[196:199], v[86:89], v[106:109], v[196:199]
	ds_read_b128 v[106:109], v112 offset:20736
	v_fmac_f32_e32 v219, v225, v129
	v_max_i32_e32 v224, 0, v6
	v_fmac_f32_e32 v219, v224, v130
	v_mfma_f32_16x16x32_bf16 v[184:187], v[74:77], v[102:105], v[184:187]
	v_max_i32_e32 v225, 0, v7
	v_fmac_f32_e32 v219, v225, v131
	v_max_i32_e32 v224, 0, v12
	v_mfma_f32_16x16x32_bf16 v[192:195], v[94:97], v[102:105], v[192:195]
	ds_read_b128 v[102:105], v112 offset:22528
	v_fmac_f32_e32 v219, v224, v132
	v_max_i32_e32 v225, 0, v13
	v_fmac_f32_e32 v219, v225, v133
	v_mfma_f32_16x16x32_bf16 v[188:191], v[74:77], v[98:101], v[188:191]
	v_max_i32_e32 v224, 0, v14
	v_fmac_f32_e32 v219, v224, v134
	v_mfma_f32_16x16x32_bf16 v[196:199], v[94:97], v[98:101], v[196:199]
	ds_read_b128 v[98:101], v112 offset:22784
	v_max_i32_e32 v225, 0, v15
	v_fmac_f32_e32 v219, v225, v135
	s_waitcnt lgkmcnt(7)
	v_mfma_f32_16x16x32_bf16 v[0:3], v[58:61], v[160:163], 0
	v_mfma_f32_16x16x32_bf16 v[8:11], v[28:31], v[160:163], 0
	s_waitcnt lgkmcnt(6)
	v_mfma_f32_16x16x32_bf16 v[4:7], v[58:61], v[164:167], 0
	v_mfma_f32_16x16x32_bf16 v[12:15], v[28:31], v[164:167], 0
	v_max_i32_e32 v226, 0, v184
	v_fma_f32 v220, v226, v136, 0
	s_waitcnt lgkmcnt(5)
	v_mfma_f32_16x16x32_bf16 v[0:3], v[16:19], v[168:171], v[0:3]
	v_max_i32_e32 v227, 0, v185
	v_fmac_f32_e32 v220, v227, v137
	v_mfma_f32_16x16x32_bf16 v[8:11], v[50:53], v[168:171], v[8:11]
	v_max_i32_e32 v226, 0, v186
	v_fmac_f32_e32 v220, v226, v138
	s_waitcnt lgkmcnt(4)
	v_mfma_f32_16x16x32_bf16 v[4:7], v[16:19], v[172:175], v[4:7]
	v_max_i32_e32 v227, 0, v187
	v_fmac_f32_e32 v220, v227, v139
	v_mfma_f32_16x16x32_bf16 v[12:15], v[50:53], v[172:175], v[12:15]
	v_max_i32_e32 v226, 0, v192
	v_fmac_f32_e32 v220, v226, v140
	s_waitcnt lgkmcnt(3)
	v_mfma_f32_16x16x32_bf16 v[0:3], v[20:23], v[176:179], v[0:3]
	v_max_i32_e32 v227, 0, v193
	v_fmac_f32_e32 v220, v227, v141
	v_mfma_f32_16x16x32_bf16 v[8:11], v[54:57], v[176:179], v[8:11]
	v_max_i32_e32 v226, 0, v194
	v_fmac_f32_e32 v220, v226, v142
	v_max_i32_e32 v227, 0, v195
	s_waitcnt lgkmcnt(2)
	v_mfma_f32_16x16x32_bf16 v[4:7], v[20:23], v[106:109], v[4:7]
	v_fmac_f32_e32 v220, v227, v143
	v_max_i32_e32 v226, 0, v188
	v_fma_f32 v221, v226, v136, 0
	v_mfma_f32_16x16x32_bf16 v[12:15], v[54:57], v[106:109], v[12:15]
	v_max_i32_e32 v227, 0, v189
	v_fmac_f32_e32 v221, v227, v137
	v_max_i32_e32 v226, 0, v190
	s_waitcnt lgkmcnt(1)
	v_mfma_f32_16x16x32_bf16 v[0:3], v[24:27], v[102:105], v[0:3]
	v_fmac_f32_e32 v221, v226, v138
	v_max_i32_e32 v227, 0, v191
	v_fmac_f32_e32 v221, v227, v139
	v_mfma_f32_16x16x32_bf16 v[8:11], v[62:65], v[102:105], v[8:11]
	v_max_i32_e32 v226, 0, v196
	v_fmac_f32_e32 v221, v226, v140
	v_max_i32_e32 v227, 0, v197
	s_waitcnt lgkmcnt(0)
; __device__ __forceinline__ void ph_indexer(const Params& p, char* shm) {
;     ...
;           IDX_TILE(ktp * 2, pr0);
;           __builtin_amdgcn_sched_barrier(0);
;           IDX_TILE(ktp * 2 + 1, pr1);
;           __builtin_amdgcn_sched_barrier(0);
;     ...
; #pragma unroll
;           for (int q = 0; q < 2; ++q) {
;             const float mine = half ? pr1[q] : pr0[q];
;             const float send = half ? pr0[q] : pr1[q];
;             const float recv = __shfl_xor(send, 32);
;             p.SC[(rowb + wid * 2 + q) * L + st * 128 + ktp * 64 + lane] = mine + recv;
	v_mfma_f32_16x16x32_bf16 v[4:7], v[24:27], v[98:101], v[4:7]
	v_fmac_f32_e32 v221, v227, v141
	v_max_i32_e32 v226, 0, v198
	v_fmac_f32_e32 v221, v226, v142
	v_mfma_f32_16x16x32_bf16 v[12:15], v[62:65], v[98:101], v[12:15]
	v_max_i32_e32 v227, 0, v199
	v_fmac_f32_e32 v221, v227, v143
	v_mfma_f32_16x16x32_bf16 v[184:187], v[90:93], v[160:163], 0
	s_nop 1
	v_permlane16_swap_b32_e32 v200, v201
	v_permlane16_swap_b32_e32 v218, v219
	v_permlane16_swap_b32_e32 v202, v203
	v_mfma_f32_16x16x32_bf16 v[192:195], v[78:81], v[160:163], 0
	ds_read_b128 v[160:163], v112 offset:24576
	v_permlane16_swap_b32_e32 v220, v221
	v_add_f32_e32 v200, v200, v201
	v_add_f32_e32 v218, v218, v219
	v_add_f32_e32 v202, v202, v203
	v_mfma_f32_16x16x32_bf16 v[188:191], v[90:93], v[164:167], 0
	v_add_f32_e32 v220, v220, v221
	s_nop 1
	v_permlane32_swap_b32_e32 v200, v218
	v_permlane32_swap_b32_e32 v202, v220
	v_mfma_f32_16x16x32_bf16 v[196:199], v[78:81], v[164:167], 0
	ds_read_b128 v[164:167], v112 offset:24832
	v_add_f32_e32 v200, v200, v218
	v_add_f32_e32 v202, v202, v220
	global_store_dword v[228:229], v200, off nt
	global_store_dword v[230:231], v202, off nt
	v_mfma_f32_16x16x32_bf16 v[184:187], v[66:69], v[168:171], v[184:187]
	v_max_i32_e32 v224, 0, v0
	v_fma_f32 v222, v224, v128, 0
	v_mfma_f32_16x16x32_bf16 v[192:195], v[82:85], v[168:171], v[192:195]
	ds_read_b128 v[168:171], v112 offset:26624
	v_max_i32_e32 v225, 0, v1
	v_fmac_f32_e32 v222, v225, v129
	v_mfma_f32_16x16x32_bf16 v[188:191], v[66:69], v[172:175], v[188:191]
	v_max_i32_e32 v224, 0, v2
	v_fmac_f32_e32 v222, v224, v130
	v_max_i32_e32 v225, 0, v3
	v_mfma_f32_16x16x32_bf16 v[196:199], v[82:85], v[172:175], v[196:199]
	ds_read_b128 v[172:175], v112 offset:26880
	v_fmac_f32_e32 v222, v225, v131
	v_max_i32_e32 v224, 0, v8
	v_fmac_f32_e32 v222, v224, v132
	v_mfma_f32_16x16x32_bf16 v[184:187], v[70:73], v[176:179], v[184:187]
	v_max_i32_e32 v225, 0, v9
	v_fmac_f32_e32 v222, v225, v133
	v_max_i32_e32 v224, 0, v10
	v_mfma_f32_16x16x32_bf16 v[192:195], v[86:89], v[176:179], v[192:195]
	ds_read_b128 v[176:179], v112 offset:28672
	v_fmac_f32_e32 v222, v224, v134
	v_max_i32_e32 v225, 0, v11
	v_fmac_f32_e32 v222, v225, v135
	v_mfma_f32_16x16x32_bf16 v[188:191], v[70:73], v[106:109], v[188:191]
	v_max_i32_e32 v224, 0, v4
	v_fma_f32 v223, v224, v128, 0
	v_max_i32_e32 v225, 0, v5
	v_mfma_f32_16x16x32_bf16 v[196:199], v[86:89], v[106:109], v[196:199]
	ds_read_b128 v[106:109], v112 offset:28928
	v_fmac_f32_e32 v223, v225, v129
	v_max_i32_e32 v224, 0, v6
	v_fmac_f32_e32 v223, v224, v130
	v_mfma_f32_16x16x32_bf16 v[184:187], v[74:77], v[102:105], v[184:187]
	v_max_i32_e32 v225, 0, v7
	v_fmac_f32_e32 v223, v225, v131
	v_max_i32_e32 v224, 0, v12
	v_mfma_f32_16x16x32_bf16 v[192:195], v[94:97], v[102:105], v[192:195]
	ds_read_b128 v[102:105], v112 offset:30720
	v_fmac_f32_e32 v223, v224, v132
	v_max_i32_e32 v225, 0, v13
	v_fmac_f32_e32 v223, v225, v133
	v_mfma_f32_16x16x32_bf16 v[188:191], v[74:77], v[98:101], v[188:191]
	v_max_i32_e32 v224, 0, v14
	v_fmac_f32_e32 v223, v224, v134
	v_mfma_f32_16x16x32_bf16 v[196:199], v[94:97], v[98:101], v[196:199]
	ds_read_b128 v[98:101], v112 offset:30976
	v_max_i32_e32 v225, 0, v15
	v_fmac_f32_e32 v223, v225, v135
	s_waitcnt lgkmcnt(7)
	v_mfma_f32_16x16x32_bf16 v[0:3], v[58:61], v[160:163], 0
	v_mfma_f32_16x16x32_bf16 v[8:11], v[28:31], v[160:163], 0
	s_waitcnt lgkmcnt(6)
	v_mfma_f32_16x16x32_bf16 v[4:7], v[58:61], v[164:167], 0
	v_mfma_f32_16x16x32_bf16 v[12:15], v[28:31], v[164:167], 0
	v_max_i32_e32 v226, 0, v184
	v_fma_f32 v202, v226, v136, 0
	s_waitcnt lgkmcnt(5)
	v_mfma_f32_16x16x32_bf16 v[0:3], v[16:19], v[168:171], v[0:3]
	v_max_i32_e32 v227, 0, v185
	v_fmac_f32_e32 v202, v227, v137
	v_mfma_f32_16x16x32_bf16 v[8:11], v[50:53], v[168:171], v[8:11]
	v_max_i32_e32 v226, 0, v186
	v_fmac_f32_e32 v202, v226, v138
	s_waitcnt lgkmcnt(4)
; __device__ __forceinline__ void ph_indexer(const Params& p, char* shm) {
;     ...
;           IDX_TILE(ktp * 2, pr0);
;           __builtin_amdgcn_sched_barrier(0);
;           IDX_TILE(ktp * 2 + 1, pr1);
;           __builtin_amdgcn_sched_barrier(0);
;     ...
; #pragma unroll
;           for (int q = 0; q < 2; ++q) {
;             const float mine = half ? pr1[q] : pr0[q];
;             const float send = half ? pr0[q] : pr1[q];
;             const float recv = __shfl_xor(send, 32);
;             p.SC[(rowb + wid * 2 + q) * L + st * 128 + ktp * 64 + lane] = mine + recv;
;           }
;         }
	v_mfma_f32_16x16x32_bf16 v[4:7], v[16:19], v[172:175], v[4:7]
	v_max_i32_e32 v227, 0, v187
	v_fmac_f32_e32 v202, v227, v139
	v_mfma_f32_16x16x32_bf16 v[12:15], v[50:53], v[172:175], v[12:15]
	v_max_i32_e32 v226, 0, v192
	v_fmac_f32_e32 v202, v226, v140
	s_waitcnt lgkmcnt(3)
	v_mfma_f32_16x16x32_bf16 v[0:3], v[20:23], v[176:179], v[0:3]
	v_max_i32_e32 v227, 0, v193
	v_fmac_f32_e32 v202, v227, v141
	v_mfma_f32_16x16x32_bf16 v[8:11], v[54:57], v[176:179], v[8:11]
	v_max_i32_e32 v226, 0, v194
	v_fmac_f32_e32 v202, v226, v142
	v_max_i32_e32 v227, 0, v195
	s_waitcnt lgkmcnt(2)
	v_mfma_f32_16x16x32_bf16 v[4:7], v[20:23], v[106:109], v[4:7]
	v_fmac_f32_e32 v202, v227, v143
	v_max_i32_e32 v226, 0, v188
	v_fma_f32 v203, v226, v136, 0
	v_mfma_f32_16x16x32_bf16 v[12:15], v[54:57], v[106:109], v[12:15]
	v_max_i32_e32 v227, 0, v189
	v_fmac_f32_e32 v203, v227, v137
	v_max_i32_e32 v226, 0, v190
	s_waitcnt lgkmcnt(1)
	v_mfma_f32_16x16x32_bf16 v[0:3], v[24:27], v[102:105], v[0:3]
	v_fmac_f32_e32 v203, v226, v138
	v_max_i32_e32 v227, 0, v191
	v_fmac_f32_e32 v203, v227, v139
	v_mfma_f32_16x16x32_bf16 v[8:11], v[62:65], v[102:105], v[8:11]
	v_max_i32_e32 v226, 0, v196
	v_fmac_f32_e32 v203, v226, v140
	v_max_i32_e32 v227, 0, v197
	s_waitcnt lgkmcnt(0)
	v_mfma_f32_16x16x32_bf16 v[4:7], v[24:27], v[98:101], v[4:7]
	v_fmac_f32_e32 v203, v227, v141
	v_max_i32_e32 v226, 0, v198
	v_fmac_f32_e32 v203, v226, v142
	v_mfma_f32_16x16x32_bf16 v[12:15], v[62:65], v[98:101], v[12:15]
	v_max_i32_e32 v227, 0, v199
	v_fmac_f32_e32 v203, v227, v143
	v_mfma_f32_16x16x32_bf16 v[184:187], v[90:93], v[160:163], 0
	v_mfma_f32_16x16x32_bf16 v[192:195], v[78:81], v[160:163], 0
	v_mfma_f32_16x16x32_bf16 v[188:191], v[90:93], v[164:167], 0
	v_mfma_f32_16x16x32_bf16 v[196:199], v[78:81], v[164:167], 0
	v_mfma_f32_16x16x32_bf16 v[184:187], v[66:69], v[168:171], v[184:187]
	v_max_i32_e32 v224, 0, v0
	v_fma_f32 v218, v224, v128, 0
	v_mfma_f32_16x16x32_bf16 v[192:195], v[82:85], v[168:171], v[192:195]
	v_max_i32_e32 v225, 0, v1
	v_fmac_f32_e32 v218, v225, v129
	v_mfma_f32_16x16x32_bf16 v[188:191], v[66:69], v[172:175], v[188:191]
	v_max_i32_e32 v224, 0, v2
	v_fmac_f32_e32 v218, v224, v130
	v_max_i32_e32 v225, 0, v3
	v_mfma_f32_16x16x32_bf16 v[196:199], v[82:85], v[172:175], v[196:199]
	v_fmac_f32_e32 v218, v225, v131
	v_max_i32_e32 v224, 0, v8
	v_fmac_f32_e32 v218, v224, v132
	v_mfma_f32_16x16x32_bf16 v[184:187], v[70:73], v[176:179], v[184:187]
	v_max_i32_e32 v225, 0, v9
	v_fmac_f32_e32 v218, v225, v133
	v_max_i32_e32 v224, 0, v10
	v_mfma_f32_16x16x32_bf16 v[192:195], v[86:89], v[176:179], v[192:195]
	v_fmac_f32_e32 v218, v224, v134
	v_max_i32_e32 v225, 0, v11
	v_fmac_f32_e32 v218, v225, v135
	v_mfma_f32_16x16x32_bf16 v[188:191], v[70:73], v[106:109], v[188:191]
	v_max_i32_e32 v224, 0, v4
	v_fma_f32 v219, v224, v128, 0
	v_max_i32_e32 v225, 0, v5
	v_mfma_f32_16x16x32_bf16 v[196:199], v[86:89], v[106:109], v[196:199]
	v_fmac_f32_e32 v219, v225, v129
	v_max_i32_e32 v224, 0, v6
	v_fmac_f32_e32 v219, v224, v130
	v_mfma_f32_16x16x32_bf16 v[184:187], v[74:77], v[102:105], v[184:187]
	v_max_i32_e32 v225, 0, v7
	v_fmac_f32_e32 v219, v225, v131
	v_max_i32_e32 v224, 0, v12
	v_mfma_f32_16x16x32_bf16 v[192:195], v[94:97], v[102:105], v[192:195]
	v_fmac_f32_e32 v219, v224, v132
	v_max_i32_e32 v225, 0, v13
	v_fmac_f32_e32 v219, v225, v133
	v_mfma_f32_16x16x32_bf16 v[188:191], v[74:77], v[98:101], v[188:191]
	v_max_i32_e32 v224, 0, v14
	v_fmac_f32_e32 v219, v224, v134
	v_mfma_f32_16x16x32_bf16 v[196:199], v[94:97], v[98:101], v[196:199]
	v_max_i32_e32 v225, 0, v15
	v_fmac_f32_e32 v219, v225, v135
	s_cmp_lg_u32 s20, s22
	s_cbranch_scc0 .Lidx_flush_s1
	s_mov_b32 s4, s20
	s_branch .LBB0_935
